# attention unit finish: the four gate-piece loads hoisted to the top of the finish into free registers, consumers behind counted vmcnt(3) instead of four serialized vmcnt(0) round trips
# baseline (speedup 1.0000x reference)
.LBB0_356:
	s_lshl_b64 s[0:1], s[10:11], 1
	v_readlane_b32 s4, v253, 55
	v_readlane_b32 s5, v253, 56
	s_add_u32 s0, s4, s0
	s_addc_u32 s1, s5, s1
	v_lshlrev_b64 v[152:153], 11, v[100:101]
	v_lshlrev_b64 v[154:155], 11, v[96:97]
	v_lshl_add_u64 v[152:153], s[0:1], 0, v[152:153]
	v_lshl_add_u64 v[154:155], s[0:1], 0, v[154:155]
	v_lshl_add_u64 v[152:153], v[152:153], 0, v[208:209]
	v_lshl_add_u64 v[154:155], v[154:155], 0, v[208:209]
	global_load_dwordx4 v[156:159], v[152:153], off
	global_load_dwordx4 v[160:163], v[152:153], off offset:64
	global_load_dwordx4 v[164:167], v[154:155], off
	global_load_dwordx4 v[168:171], v[154:155], off offset:64
	ds_bpermute_b32 v17, v132, v16
	s_waitcnt lgkmcnt(0)
	v_add_f32_e32 v16, v16, v17
	ds_bpermute_b32 v17, v133, v16
	s_add_i32 s24, s24, 1
	v_readlane_b32 s4, v253, 57
	v_readlane_b32 s5, v253, 58
	s_waitcnt lgkmcnt(0)
	v_add_f32_e32 v16, v16, v17
	v_div_scale_f32 v17, s[10:11], v16, v16, 1.0
	v_rcp_f32_e32 v18, v17
	s_nop 0
	v_fma_f32 v19, -v17, v18, 1.0
	v_fmac_f32_e32 v18, v19, v18
	v_div_scale_f32 v19, vcc, 1.0, v16, 1.0
	v_mul_f32_e32 v20, v19, v18
	v_fma_f32 v21, -v17, v20, v19
	v_fmac_f32_e32 v20, v21, v18
	v_fma_f32 v17, -v17, v20, v19
	v_div_fmas_f32 v17, v17, v18, v20
	s_waitcnt vmcnt(5)
	v_div_fixup_f32 v32, v17, v16, 1.0
	v_lshlrev_b64 v[16:17], 11, v[100:101]
	v_lshl_add_u64 v[16:17], s[0:1], 0, v[16:17]
	v_lshl_add_u64 v[28:29], v[16:17], 0, v[208:209]
	v_mul_f32_e32 v20, v48, v32
	v_mul_f32_e32 v22, v52, v32
	v_mul_f32_e32 v21, v49, v32
	v_mul_f32_e32 v23, v53, v32
	v_permlane16_swap_b32_e32 v20, v22
	s_nop 0
	v_permlane16_swap_b32_e32 v21, v23
	v_mul_f32_e32 v24, v50, v32
	v_mul_f32_e32 v26, v54, v32
	v_mul_f32_e32 v25, v51, v32
	v_mul_f32_e32 v27, v55, v32
	v_permlane16_swap_b32_e32 v24, v26
	s_nop 0
	v_permlane16_swap_b32_e32 v25, v27
	s_waitcnt vmcnt(3)
	v_mov_b64_e32 v[16:17], v[156:157]
	v_mov_b64_e32 v[18:19], v[158:159]
	v_lshlrev_b32_e32 v30, 16, v16
	v_and_b32_e32 v31, 0xffff0000, v16
	v_pk_mul_f32 v[20:21], v[20:21], v[30:31]
	s_nop 0
	v_cvt_pk_bf16_f32 v16, v20, v21
	v_lshlrev_b32_e32 v20, 16, v17
	v_and_b32_e32 v21, 0xffff0000, v17
	v_pk_mul_f32 v[20:21], v[24:25], v[20:21]
	v_mul_f32_e32 v24, v42, v32
	v_cvt_pk_bf16_f32 v17, v20, v21
	v_lshlrev_b32_e32 v20, 16, v18
	v_and_b32_e32 v21, 0xffff0000, v18
	v_pk_mul_f32 v[20:21], v[22:23], v[20:21]
	v_mul_f32_e32 v22, v44, v32
	v_cvt_pk_bf16_f32 v18, v20, v21
	v_lshlrev_b32_e32 v20, 16, v19
	v_and_b32_e32 v21, 0xffff0000, v19
	v_pk_mul_f32 v[20:21], v[26:27], v[20:21]
	v_mul_f32_e32 v23, v45, v32
	v_cvt_pk_bf16_f32 v19, v20, v21
	global_store_dwordx4 v[28:29], v[16:19], off
	v_mul_f32_e32 v20, v40, v32
	v_mul_f32_e32 v21, v41, v32
	s_nop 0
	v_permlane16_swap_b32_e32 v20, v22
	v_permlane16_swap_b32_e32 v21, v23
	v_mul_f32_e32 v26, v46, v32
	v_mul_f32_e32 v25, v43, v32
	v_mul_f32_e32 v27, v47, v32
	v_permlane16_swap_b32_e32 v24, v26
	s_nop 0
	v_permlane16_swap_b32_e32 v25, v27
	s_waitcnt vmcnt(3)
	v_mov_b64_e32 v[16:17], v[160:161]
	v_mov_b64_e32 v[18:19], v[162:163]
	v_lshlrev_b32_e32 v30, 16, v16
	v_and_b32_e32 v31, 0xffff0000, v16
	v_pk_mul_f32 v[20:21], v[20:21], v[30:31]
	s_nop 0
	v_cvt_pk_bf16_f32 v16, v20, v21
	v_lshlrev_b32_e32 v20, 16, v17
	v_and_b32_e32 v21, 0xffff0000, v17
	v_pk_mul_f32 v[20:21], v[24:25], v[20:21]
	s_nop 0
	v_cvt_pk_bf16_f32 v17, v20, v21
	v_lshlrev_b32_e32 v20, 16, v18
	v_and_b32_e32 v21, 0xffff0000, v18
	v_pk_mul_f32 v[20:21], v[22:23], v[20:21]
	s_nop 0
	v_cvt_pk_bf16_f32 v18, v20, v21
	v_lshlrev_b32_e32 v20, 16, v19
	v_and_b32_e32 v21, 0xffff0000, v19
	v_pk_mul_f32 v[20:21], v[26:27], v[20:21]
	s_nop 0
	v_cvt_pk_bf16_f32 v19, v20, v21
	global_store_dwordx4 v[28:29], v[16:19], off offset:64
	ds_bpermute_b32 v16, v132, v99
	s_waitcnt lgkmcnt(0)
	v_add_f32_e32 v16, v99, v16
	ds_bpermute_b32 v17, v133, v16
	s_waitcnt lgkmcnt(0)
	v_add_f32_e32 v16, v16, v17
	v_div_scale_f32 v17, s[10:11], v16, v16, 1.0
	v_rcp_f32_e32 v18, v17
	s_nop 0
	v_fma_f32 v19, -v17, v18, 1.0
	v_fmac_f32_e32 v18, v19, v18
	v_div_scale_f32 v19, vcc, 1.0, v16, 1.0
	v_mul_f32_e32 v20, v19, v18
	v_fma_f32 v21, -v17, v20, v19
	v_fmac_f32_e32 v20, v21, v18
	v_fma_f32 v17, -v17, v20, v19
	v_div_fmas_f32 v17, v17, v18, v20
	v_div_fixup_f32 v24, v17, v16, 1.0
	v_lshlrev_b64 v[16:17], 11, v[96:97]
	v_lshl_add_u64 v[16:17], s[0:1], 0, v[16:17]
	v_mul_f32_e32 v20, v8, v24
	v_mul_f32_e32 v21, v9, v24
	v_lshl_add_u64 v[8:9], v[16:17], 0, v[208:209]
	v_mul_f32_e32 v18, v12, v24
	v_mul_f32_e32 v19, v13, v24
	v_mul_f32_e32 v22, v10, v24
	v_mul_f32_e32 v23, v11, v24
	v_permlane16_swap_b32_e32 v18, v20
	v_permlane16_swap_b32_e32 v19, v21
	v_mul_f32_e32 v14, v14, v24
	v_mul_f32_e32 v15, v15, v24
	s_nop 0
	v_permlane16_swap_b32_e32 v14, v22
	v_permlane16_swap_b32_e32 v15, v23
	s_mul_i32 s0, s24, s54
	s_add_i32 s11, s0, s4
	s_cmpk_gt_i32 s11, 0x47f
	s_waitcnt vmcnt(3)
	v_mov_b64_e32 v[10:11], v[164:165]
	v_mov_b64_e32 v[12:13], v[166:167]
	v_lshlrev_b32_e32 v16, 16, v10
	v_and_b32_e32 v17, 0xffff0000, v10
	v_pk_mul_f32 v[16:17], v[18:19], v[16:17]
	s_nop 0
	v_cvt_pk_bf16_f32 v10, v16, v17
	v_lshlrev_b32_e32 v16, 16, v11
	v_and_b32_e32 v17, 0xffff0000, v11
	v_pk_mul_f32 v[14:15], v[14:15], v[16:17]
	s_nop 0
	v_cvt_pk_bf16_f32 v11, v14, v15
	v_lshlrev_b32_e32 v14, 16, v12
	v_and_b32_e32 v15, 0xffff0000, v12
	v_pk_mul_f32 v[14:15], v[20:21], v[14:15]
	s_nop 0
	v_cvt_pk_bf16_f32 v12, v14, v15
	v_lshlrev_b32_e32 v14, 16, v13
	v_and_b32_e32 v15, 0xffff0000, v13
	v_pk_mul_f32 v[14:15], v[22:23], v[14:15]
	s_nop 0
	v_cvt_pk_bf16_f32 v13, v14, v15
	global_store_dwordx4 v[8:9], v[10:13], off
	v_mul_f32_e32 v14, v0, v24
	v_mul_f32_e32 v15, v1, v24
	v_mul_f32_e32 v12, v2, v24
	v_mul_f32_e32 v13, v3, v24
	v_mul_f32_e32 v10, v4, v24
	v_mul_f32_e32 v11, v5, v24
	s_nop 0
	v_permlane16_swap_b32_e32 v14, v10
	v_permlane16_swap_b32_e32 v15, v11
	v_mul_f32_e32 v4, v6, v24
	v_mul_f32_e32 v5, v7, v24
	s_nop 0
	v_permlane16_swap_b32_e32 v12, v4
	v_permlane16_swap_b32_e32 v13, v5
	s_waitcnt vmcnt(3)
	v_mov_b64_e32 v[0:1], v[168:169]
	v_mov_b64_e32 v[2:3], v[170:171]
	v_lshlrev_b32_e32 v6, 16, v0
	v_and_b32_e32 v7, 0xffff0000, v0
	v_pk_mul_f32 v[6:7], v[14:15], v[6:7]
	s_nop 0
	v_cvt_pk_bf16_f32 v0, v6, v7
	v_lshlrev_b32_e32 v6, 16, v1
	v_and_b32_e32 v7, 0xffff0000, v1
	v_pk_mul_f32 v[6:7], v[12:13], v[6:7]
	s_nop 0
	v_cvt_pk_bf16_f32 v1, v6, v7
	v_lshlrev_b32_e32 v6, 16, v2
	v_and_b32_e32 v7, 0xffff0000, v2
	v_pk_mul_f32 v[6:7], v[10:11], v[6:7]
	s_nop 0
	v_cvt_pk_bf16_f32 v2, v6, v7
	v_lshlrev_b32_e32 v6, 16, v3
	v_and_b32_e32 v7, 0xffff0000, v3
	v_pk_mul_f32 v[4:5], v[4:5], v[6:7]
	s_nop 0
	v_cvt_pk_bf16_f32 v3, v4, v5
	global_store_dwordx4 v[8:9], v[0:3], off offset:64
	s_cbranch_scc1 .LBB0_381
